# same-layer windows, in-proj-tail window 4 iterations (A=4,P=3,B=2)
# baseline (speedup 1.0000x reference)
; #define LAS __attribute__((address_space(3)))
; __device__ __forceinline__ void convert_layer_static(const PT& a, LAS unsigned char* lds, int l, int gw, int NGW, int wave, int lane, int r_end = IT_LAYER) {
;     for (int r = 2 * gw; r < r_end; r += 2 * NGW) cv_pair(a, lds, l, r, wave, lane);
; }
; __device__ __forceinline__ void prologue_a(const PT& a, LAS unsigned char* lds) {
;     ...
;     convert_layer_static(a, lds, 0, gw, NGW, wave, lane);
;     for (int cl_ = 1; cl_ < DEPTH; ++cl_) convert_layer_static(a, lds, cl_, gw, NGW, wave, lane, CV_PRO_ITEMS);
.LBB0_22:
	s_or_saveexec_b64 s[12:13], s[0:1]
	v_lshlrev_b32_e32 v109, 1, v66
	v_readlane_b32 s0, v252, 4
	v_mul_lo_u32 v3, v12, s6
	s_lshl_b32 s17, s0, 4
	v_add_u32_e32 v115, 0, v3
	v_lshlrev_b32_e32 v111, 5, v109
	v_readlane_b32 s1, v252, 5
	s_xor_b64 exec, exec, s[12:13]
	s_cbranch_execz .LBB0_110
	v_and_b32_e32 v74, 28, v68
	v_and_b32_e32 v76, 56, v2
	v_mov_b32_e32 v79, 0
	v_lshl_add_u32 v3, v74, 2, v115
	v_mul_u32_u24_e32 v121, 0x84, v67
	v_mul_u32_u24_e32 v113, 0x84, v76
	v_lshlrev_b32_e32 v2, 2, v67
	v_mov_b32_e32 v75, v79
	v_or_b32_e32 v69, 8, v67
	v_or_b32_e32 v97, 16, v67
	v_or_b32_e32 v99, 24, v67
	v_or_b32_e32 v101, 32, v67
	v_or_b32_e32 v103, 40, v67
	v_or_b32_e32 v105, 48, v67
	v_or_b32_e32 v107, 56, v67
	v_mov_b32_e32 v77, v79
	v_add3_u32 v117, v115, v113, v2
	v_lshlrev_b32_e32 v119, 5, v109
	s_lshl_b32 s36, s17, 5
	s_mov_b64 s[18:19], 0
	s_movk_i32 s37, 0x393f
	s_movk_i32 s38, 0x453f
	s_movk_i32 s39, 0x4d3f
	s_movk_i32 s40, 0x793f
	s_movk_i32 s41, 0x15ff
	s_movk_i32 s42, 0xba3
	s_movk_i32 s43, 0x1600
	s_movk_i32 s44, 0x3ff
	s_mov_b64 s[20:21], 0xea00000
	s_mov_b32 s45, 0x478bbced
	s_movk_i32 s46, 0x9f
	s_movk_i32 s47, 0x109
	v_lshlrev_b32_e32 v78, 2, v74
	v_add_u32_e32 v123, v3, v121
	v_lshlrev_b32_e32 v80, 1, v76
	s_mov_b32 s48, 0x473f
	v_readlane_b32 s100, v252, 4
	s_cmp_eq_u32 s100, 0x100
	s_cselect_b32 s48, s48, 0x8f3f
	v_mov_b32_e32 v127, 0xea00
	v_mov_b32_e32 v129, 5
	v_mov_b32_e32 v130, 0x23a40
	v_mov_b32_e32 v131, 0x23a38
	v_mov_b32_e32 v132, 6
	v_mov_b32_e32 v133, 0x80
	v_mov_b32_e32 v134, 0x23a20
	v_mov_b32_e32 v135, 0x23a18
	v_mov_b32_e32 v136, 0x23a10
	v_mov_b32_e32 v137, v109
	s_branch .LBB0_25

; #define LAS __attribute__((address_space(3)))
; __device__ __forceinline__ void convert_layer_static(const PT& a, LAS unsigned char* lds, int l, int gw, int NGW, int wave, int lane, int r_end = IT_LAYER) {
;     for (int r = 2 * gw; r < r_end; r += 2 * NGW) cv_pair(a, lds, l, r, wave, lane);
; }
; __device__ __forceinline__ void prologue_a(const PT& a, LAS unsigned char* lds) {
;     ...
;     convert_layer_static(a, lds, 0, gw, NGW, wave, lane);
;     for (int cl_ = 1; cl_ < DEPTH; ++cl_) convert_layer_static(a, lds, cl_, gw, NGW, wave, lane, CV_PRO_ITEMS);
.LBB0_110:
	s_or_b64 exec, exec, s[12:13]
	v_lshl_add_u32 v2, v74, 2, v115
	v_add_u32_e32 v3, v115, v113
	s_mov_b32 s13, 0
	v_lshl_add_u32 v113, v67, 2, v3
	v_lshl_add_u32 v115, v69, 2, v3
	v_lshl_add_u32 v117, v97, 2, v3
	v_lshl_add_u32 v119, v99, 2, v3
	s_mov_b32 s18, 1
	s_lshl_b32 s42, s17, 5
	s_movk_i32 s43, 0x393f
	s_movk_i32 s44, 0x453f
	s_movk_i32 s45, 0x4d3f
	s_movk_i32 s46, 0x793f
	s_movk_i32 s47, 0x15ff
	s_movk_i32 s48, 0xba3
	s_movk_i32 s49, 0x1600
	s_movk_i32 s50, 0x3ff
	v_mov_b32_e32 v79, 0
	s_mov_b64 s[20:21], 0xea00000
	s_mov_b32 s51, 0x478bbced
	s_movk_i32 s52, 0x9f
	s_movk_i32 s53, 0x109
	v_add_u32_e32 v121, v2, v121
	v_lshlrev_b64 v[76:77], 1, v[76:77]
	s_mov_b32 s54, 0x373f
	v_readlane_b32 s100, v252, 4
	s_cmp_eq_u32 s100, 0x100
	s_cselect_b32 s54, s54, 0x8f3f
	v_mov_b32_e32 v123, 0xea00
	v_mov_b32_e32 v125, 5
	v_mov_b32_e32 v128, 0x23a40
	v_mov_b32_e32 v129, 0x23a38
	v_mov_b32_e32 v130, 6
	v_mov_b32_e32 v131, 0x80
	v_mov_b32_e32 v132, 0x23a20
	v_mov_b32_e32 v133, 0x23a18
	v_mov_b32_e32 v134, 0x23a10
	s_branch .LBB0_112

; __device__ __forceinline__ int opaque_tid() { int t = threadIdx.x; asm volatile("" : "+v"(t)); return t; }
;     for (int it = 0; it < budget; ++it) {
;         unsigned r = 0; if (lane == 0) r = __hip_atomic_fetch_add(ctr, 2u, __ATOMIC_RELAXED, __HIP_MEMORY_SCOPE_AGENT);
;         r = (unsigned)__builtin_amdgcn_readfirstlane((int)r) + (unsigned)CV_PRO_ITEMS;
;         if (r >= (unsigned)IT_LAYER) break;
;         cv_pair(a, lds, l, (int)r, wave, lane);
;     }
; }
; __global__ void __launch_bounds__(NTHREADS, 2) mk_fwd(Args args) {
;     ...
;             if (l + 1 < DEPTH && !(G >= 256 && bid < 128)) { __syncthreads(); const int tid_ = opaque_tid(); convert_layer_queue(pt, lds, l + 1, cvq, tid_ >> 6, tid_ & 63); }
.LBB0_560:
	v_readlane_b32 s0, v252, 4
	s_cmp_lg_u32 s0, 0x100
	s_cbranch_scc1 .LcvqA_ret
	v_readlane_b32 s0, v252, 0
	v_readlane_b32 s36, v255, 0
	s_cmp_lt_u32 s0, 64
	s_cbranch_scc1 .LcvqA_ret
	s_mov_b32 s64, s36
	v_readlane_b32 s0, v254, 53
	v_readlane_b32 s1, v254, 54
	s_mov_b32 s3, s1
	s_lshl_b32 s2, s36, 6
	s_lshl_b64 s[0:1], s[2:3], 2
	v_readlane_b32 s4, v254, 60
	v_readlane_b32 s5, v254, 61
	s_add_u32 s0, s4, s0
	s_addc_u32 s1, s5, s1
	s_add_u32 s0, s0, 0x8000
	s_addc_u32 s1, s1, 0
	s_add_i32 s2, s36, 0
	s_mul_hi_u32 s33, s2, 0x2c00000
	s_mul_i32 s34, s2, 0x2c00000
	s_mul_hi_u32 s35, s2, 0x1600000
	s_mul_i32 s50, s2, 0x1600000
	s_lshl_b32 s6, s2, 11
	s_mov_b32 s7, s3
	s_lshl_b64 s[8:9], s[2:3], 24
	s_lshl_b64 s[10:11], s[2:3], 23
	s_mul_hi_u32 s51, s2, 0xc00000
	s_mul_i32 s52, s2, 0xc00000
	s_mul_hi_u32 s53, s2, 0x7280000
	s_mul_i32 s54, s2, 0x7280000
	s_mul_hi_u32 s55, s2, 0x3a00000
	v_writelane_b32 v254, s2, 53
	v_mov_b32_e32 v2, v0
	s_mul_i32 s56, s2, 0x3a00000
	v_writelane_b32 v254, s3, 54
	s_waitcnt vmcnt(0) lgkmcnt(0)
	s_barrier
	s_movk_i32 s2, 0x4200
	v_lshrrev_b32_e32 v1, 6, v2
	v_and_b32_e32 v3, 63, v2
	v_readfirstlane_b32 s100, v1
	v_readlane_b32 s101, v252, 0
	s_sub_u32 s101, s101, 64
	s_lshl_b32 s101, s101, 3
	s_add_u32 s100, s100, s101
	s_lshl_b32 s100, s100, 1
	s_add_u32 s100, s100, 0x1000
	v_mul_lo_u32 v1, v1, s2
	v_cmp_eq_u32_e64 s[40:41], 0, v3
	v_add_u32_e32 v3, 0, v1
	v_lshlrev_b32_e32 v1, 2, v2
	v_and_b32_e32 v66, 28, v1
	v_bfe_u32 v1, v2, 3, 3
	v_lshlrev_b32_e32 v2, 3, v2
	v_and_b32_e32 v68, 56, v2
	v_lshl_add_u32 v4, v66, 2, v3
	v_mul_u32_u24_e32 v5, 0x84, v1
	v_mul_u32_u24_e32 v2, 0x84, v68
	v_lshlrev_b32_e32 v6, 2, v1
	v_or_b32_e32 v67, 8, v1
	v_or_b32_e32 v69, 16, v1
	v_or_b32_e32 v71, 24, v1
	v_or_b32_e32 v73, 32, v1
	v_or_b32_e32 v75, 40, v1
	v_or_b32_e32 v77, 48, v1
	v_or_b32_e32 v79, 56, v1
	v_add3_u32 v81, v3, v2, v6
	s_mov_b32 s57, 0x4
	v_add_u32_e32 v83, v4, v5
	s_branch .LcvqA_1381

;     __device__ __forceinline__ const float* in(int i) const { return (const float*)(const GAS float*)raw(i); }
;     __device__ __forceinline__ unsigned char* ws() const { return (unsigned char*)(GAS unsigned char*)raw(N_INPUTS + 1); }
; __device__ __forceinline__ CvItem cv_decode(const PT& a, int l, int r) {
;     unsigned char* ws = a.ws(); CvItem it;
;     if (r < IT_WIN) { const int kb = r / 458, nb = r % 458, n0 = nb * 32;
;         int drow; if (n0 < 2048) drow = n0; else if (n0 < 5120) drow = NIN_MAIN + (n0 - 2048); else if (n0 < 8512) drow = 2048 + (n0 - 5120); else drow = 5632 + (n0 - 8512);
;         it = CvItem{a.in(I_W_IN) + (size_t)l * D * NIN, NIN, kb * 64, n0, (bf16_t*)(ws + WS_WIN + l * WIN_L), D, drow, a.in(I_NORM_MIX_G) + l * D}; return it; }
;     r -= IT_WIN;
;     if (r < 3 * IT_BR) { const int br = r / IT_BR; r -= br * IT_BR; const int kb = r / 64, nb = r % 64;
;         it = CvItem{a.in(br == 0 ? I_W_BR_A : (br == 1 ? I_W_BR_B : I_W_BR_C)) + (size_t)l * 1024 * D, D, kb * 64, nb * 32, (bf16_t*)(ws + WS_WBR + l * WBR_L) + (size_t)br * D * 1024, 1024, nb * 32, nullptr}; return it; }
;     r -= 3 * IT_BR;
;     if (r < IT_OUT) { const int kb = r / 64, nb = r % 64;
;         it = CvItem{a.in(I_W_OUT) + (size_t)l * D * D, D, kb * 64, nb * 32, (bf16_t*)(ws + WS_WOUT + l * WOUT_L), D, nb * 32, nullptr}; return it; }
;     r -= IT_OUT;
;     if (r < 2 * IT_GU) { const int up = r / IT_GU; r -= up * IT_GU; const int kb = r / 176, nb = r % 176, n0 = nb * 32;
;         it = CvItem{a.in(up ? I_W_FFN_UP : I_W_FFN_GATE) + (size_t)l * D * DFF, DFF, kb * 64, n0, (bf16_t*)(ws + WS_WGU + l * WGU_L), D, 256 * (n0 / 128) + (n0 % 128) + 128 * up, a.in(I_NORM_FFN_G) + l * D}; return it; }
;     r -= 2 * IT_GU;
;     { const int kb = r / 64, nb = r % 64;
;       it = CvItem{a.in(I_W_FFN_DOWN) + (size_t)l * DFF * D, D, kb * 64, nb * 32, (bf16_t*)(ws + WS_WDN + l * WDN_L), DFF, nb * 32, nullptr}; }
;     for (int it = 0; it < budget; ++it) {
;         unsigned r = 0; if (lane == 0) r = __hip_atomic_fetch_add(ctr, 2u, __ATOMIC_RELAXED, __HIP_MEMORY_SCOPE_AGENT);
;         r = (unsigned)__builtin_amdgcn_readfirstlane((int)r) + (unsigned)CV_PRO_ITEMS;
;         if (r >= (unsigned)IT_LAYER) break;
;         cv_pair(a, lds, l, (int)r, wave, lane);
.LcvqA_1381:
	s_mov_b32 s24, s100
	s_add_u32 s100, s100, 0xc00
	s_add_i32 s24, s24, 0xffffa800
	s_cmp_lt_u32 s24, 0xffff70c0
	s_mov_b64 s[2:3], -1
	s_cbranch_scc1 .LcvqA_1380
	v_mov_b32_e32 v2, 0x23a60
	s_add_i32 s15, s24, 0x8f40
	v_add_u32_e32 v2, 0, v2
	ds_read_b64 v[2:3], v2
	s_cmpk_gt_u32 s15, 0x393f
	s_waitcnt lgkmcnt(0)
	v_readfirstlane_b32 s20, v3
	v_readfirstlane_b32 s21, v2
	s_cbranch_scc0 .LcvqA_1399
	s_cmpk_gt_u32 s15, 0x453f
	s_cbranch_scc0 .LcvqA_1396
	s_cmpk_gt_u32 s15, 0x4d3f
	s_mov_b64 s[18:19], -1
	s_cbranch_scc0 .LcvqA_1393
	s_cmpk_gt_u32 s15, 0x793f
	s_cbranch_scc0 .LcvqA_1391
	v_mov_b32_e32 v2, 0x23a48
	s_and_b32 s2, s15, 0x7fffffc0
	v_add_u32_e32 v2, 0, v2
	ds_read_b64 v[2:3], v2
	s_add_i32 s14, s2, 0xffff86c0
	s_waitcnt lgkmcnt(0)
	v_readfirstlane_b32 s3, v2
	v_readfirstlane_b32 s2, v3
	s_add_u32 s30, s3, s34
	s_addc_u32 s31, s2, s33
	s_lshl_b32 s2, s15, 5
	s_and_b32 s25, s2, 0x7e0
	s_add_u32 s2, s21, s50
	s_addc_u32 s3, s20, s35
	s_add_u32 s12, s2, 0x1ea00000
	s_addc_u32 s13, s3, 0
	s_mov_b64 s[2:3], 0

; __device__ __forceinline__ int opaque_tid() { int t = threadIdx.x; asm volatile("" : "+v"(t)); return t; }
;     for (int it = 0; it < budget; ++it) {
;         unsigned r = 0; if (lane == 0) r = __hip_atomic_fetch_add(ctr, 2u, __ATOMIC_RELAXED, __HIP_MEMORY_SCOPE_AGENT);
;         r = (unsigned)__builtin_amdgcn_readfirstlane((int)r) + (unsigned)CV_PRO_ITEMS;
;         if (r >= (unsigned)IT_LAYER) break;
;         cv_pair(a, lds, l, (int)r, wave, lane);
;     }
; }
; __global__ void __launch_bounds__(NTHREADS, 2) mk_fwd(Args args) {
;     ...
;             if (l + 1 < DEPTH && !(G >= 256 && bid < 128)) { __syncthreads(); const int tid_ = opaque_tid(); convert_layer_queue(pt, lds, l + 1, cvq, tid_ >> 6, tid_ & 63); }
.LBB0_1377:
	s_cmp_eq_u32 s64, 0x63
	v_readlane_b32 s2, v253, 61
	s_cselect_b64 s[0:1], -1, 0
	v_readlane_b32 s3, v253, 62
	s_or_b64 s[0:1], s[2:3], s[0:1]
	v_readlane_b32 s2, v252, 4
	s_cmp_lg_u32 s2, 0x100
	s_cselect_b64 s[2:3], -1, 0
	s_or_b64 s[0:1], s[0:1], s[2:3]
	v_readlane_b32 s28, v254, 55
	s_mov_b32 s36, s64
	s_and_b64 vcc, exec, s[0:1]
	v_readlane_b32 s29, v254, 56
	s_cbranch_vccnz .LBB0_1470
	v_readlane_b32 s0, v254, 53
	v_readlane_b32 s1, v254, 54
	s_mov_b32 s3, s1
	s_lshl_b32 s2, s36, 6
	s_lshl_b64 s[0:1], s[2:3], 2
	v_readlane_b32 s4, v254, 60
	v_readlane_b32 s5, v254, 61
	s_add_u32 s0, s4, s0
	s_addc_u32 s1, s5, s1
	s_add_u32 s0, s0, 0x8000
	s_addc_u32 s1, s1, 0
	s_add_i32 s2, s36, 0
	s_mul_hi_u32 s33, s2, 0x2c00000
	s_mul_i32 s34, s2, 0x2c00000
	s_mul_hi_u32 s35, s2, 0x1600000
	s_mul_i32 s50, s2, 0x1600000
	s_lshl_b32 s6, s2, 11
	s_mov_b32 s7, s3
	s_lshl_b64 s[8:9], s[2:3], 24
	s_lshl_b64 s[10:11], s[2:3], 23
	s_mul_hi_u32 s51, s2, 0xc00000
	s_mul_i32 s52, s2, 0xc00000
	s_mul_hi_u32 s53, s2, 0x7280000
	s_mul_i32 s54, s2, 0x7280000
	s_mul_hi_u32 s55, s2, 0x3a00000
	v_writelane_b32 v254, s2, 53
	v_mov_b32_e32 v2, v0
	s_mul_i32 s56, s2, 0x3a00000
	v_writelane_b32 v254, s3, 54
	s_waitcnt vmcnt(0) lgkmcnt(0)
	s_barrier
	s_movk_i32 s2, 0x4200
	v_lshrrev_b32_e32 v1, 6, v2
	v_and_b32_e32 v3, 63, v2
	v_readfirstlane_b32 s100, v1
	v_readlane_b32 s101, v252, 0
	s_sub_u32 s101, s101, 128
	s_lshl_b32 s101, s101, 3
	s_add_u32 s100, s100, s101
	s_lshl_b32 s100, s100, 1
	s_add_u32 s100, s100, 0x4000
	v_mul_lo_u32 v1, v1, s2
	v_cmp_eq_u32_e64 s[40:41], 0, v3
	v_add_u32_e32 v3, 0, v1
	v_lshlrev_b32_e32 v1, 2, v2
	v_and_b32_e32 v66, 28, v1
	v_bfe_u32 v1, v2, 3, 3
	v_lshlrev_b32_e32 v2, 3, v2
	v_and_b32_e32 v68, 56, v2
	v_lshl_add_u32 v4, v66, 2, v3
	v_mul_u32_u24_e32 v5, 0x84, v1
	v_mul_u32_u24_e32 v2, 0x84, v68
	v_lshlrev_b32_e32 v6, 2, v1
	v_or_b32_e32 v67, 8, v1
	v_or_b32_e32 v69, 16, v1
	v_or_b32_e32 v71, 24, v1
	v_or_b32_e32 v73, 32, v1
	v_or_b32_e32 v75, 40, v1
	v_or_b32_e32 v77, 48, v1
	v_or_b32_e32 v79, 56, v1
	v_add3_u32 v81, v3, v2, v6
	s_mov_b32 s57, 0x3
	v_add_u32_e32 v83, v4, v5
	s_branch .LBB0_1381

;     __device__ __forceinline__ const float* in(int i) const { return (const float*)(const GAS float*)raw(i); }
;     __device__ __forceinline__ unsigned char* ws() const { return (unsigned char*)(GAS unsigned char*)raw(N_INPUTS + 1); }
; __device__ __forceinline__ CvItem cv_decode(const PT& a, int l, int r) {
;     unsigned char* ws = a.ws(); CvItem it;
;     if (r < IT_WIN) { const int kb = r / 458, nb = r % 458, n0 = nb * 32;
;         int drow; if (n0 < 2048) drow = n0; else if (n0 < 5120) drow = NIN_MAIN + (n0 - 2048); else if (n0 < 8512) drow = 2048 + (n0 - 5120); else drow = 5632 + (n0 - 8512);
;         it = CvItem{a.in(I_W_IN) + (size_t)l * D * NIN, NIN, kb * 64, n0, (bf16_t*)(ws + WS_WIN + l * WIN_L), D, drow, a.in(I_NORM_MIX_G) + l * D}; return it; }
;     r -= IT_WIN;
;     if (r < 3 * IT_BR) { const int br = r / IT_BR; r -= br * IT_BR; const int kb = r / 64, nb = r % 64;
;         it = CvItem{a.in(br == 0 ? I_W_BR_A : (br == 1 ? I_W_BR_B : I_W_BR_C)) + (size_t)l * 1024 * D, D, kb * 64, nb * 32, (bf16_t*)(ws + WS_WBR + l * WBR_L) + (size_t)br * D * 1024, 1024, nb * 32, nullptr}; return it; }
;     r -= 3 * IT_BR;
;     if (r < IT_OUT) { const int kb = r / 64, nb = r % 64;
;         it = CvItem{a.in(I_W_OUT) + (size_t)l * D * D, D, kb * 64, nb * 32, (bf16_t*)(ws + WS_WOUT + l * WOUT_L), D, nb * 32, nullptr}; return it; }
;     r -= IT_OUT;
;     if (r < 2 * IT_GU) { const int up = r / IT_GU; r -= up * IT_GU; const int kb = r / 176, nb = r % 176, n0 = nb * 32;
;         it = CvItem{a.in(up ? I_W_FFN_UP : I_W_FFN_GATE) + (size_t)l * D * DFF, DFF, kb * 64, n0, (bf16_t*)(ws + WS_WGU + l * WGU_L), D, 256 * (n0 / 128) + (n0 % 128) + 128 * up, a.in(I_NORM_FFN_G) + l * D}; return it; }
;     r -= 2 * IT_GU;
;     { const int kb = r / 64, nb = r % 64;
;       it = CvItem{a.in(I_W_FFN_DOWN) + (size_t)l * DFF * D, D, kb * 64, nb * 32, (bf16_t*)(ws + WS_WDN + l * WDN_L), DFF, nb * 32, nullptr}; }
;     for (int it = 0; it < budget; ++it) {
;         unsigned r = 0; if (lane == 0) r = __hip_atomic_fetch_add(ctr, 2u, __ATOMIC_RELAXED, __HIP_MEMORY_SCOPE_AGENT);
;         r = (unsigned)__builtin_amdgcn_readfirstlane((int)r) + (unsigned)CV_PRO_ITEMS;
;         if (r >= (unsigned)IT_LAYER) break;
;         cv_pair(a, lds, l, (int)r, wave, lane);
.LBB0_1381:
	s_mov_b32 s24, s100
	s_add_u32 s100, s100, 0x800
	s_add_i32 s24, s24, 0xffffa800
	s_cmp_lt_u32 s24, 0xffff70c0
	s_mov_b64 s[2:3], -1
	s_cbranch_scc1 .LBB0_1380
	v_mov_b32_e32 v2, 0x23a60
	s_add_i32 s15, s24, 0x8f40
	v_add_u32_e32 v2, 0, v2
	ds_read_b64 v[2:3], v2
	s_cmpk_gt_u32 s15, 0x393f
	s_waitcnt lgkmcnt(0)
	v_readfirstlane_b32 s20, v3
	v_readfirstlane_b32 s21, v2
	s_cbranch_scc0 .LBB0_1399
	s_cmpk_gt_u32 s15, 0x453f
	s_cbranch_scc0 .LBB0_1396
	s_cmpk_gt_u32 s15, 0x4d3f
	s_mov_b64 s[18:19], -1
	s_cbranch_scc0 .LBB0_1393
	s_cmpk_gt_u32 s15, 0x793f
	s_cbranch_scc0 .LBB0_1391
	v_mov_b32_e32 v2, 0x23a48
	s_and_b32 s2, s15, 0x7fffffc0
	v_add_u32_e32 v2, 0, v2
	ds_read_b64 v[2:3], v2
	s_add_i32 s14, s2, 0xffff86c0
	s_waitcnt lgkmcnt(0)
	v_readfirstlane_b32 s3, v2
	v_readfirstlane_b32 s2, v3
	s_add_u32 s30, s3, s34
	s_addc_u32 s31, s2, s33
	s_lshl_b32 s2, s15, 5
	s_and_b32 s25, s2, 0x7e0
	s_add_u32 s2, s21, s50
	s_addc_u32 s3, s20, s35
	s_add_u32 s12, s2, 0x1ea00000
	s_addc_u32 s13, s3, 0
	s_mov_b64 s[2:3], 0
